# dense attention (mixer A): static s_setprio 1 for the second wave half during the phase (reset at the phase barrier) + QK fragment LDS reads 3-4 deep
# speedup vs baseline: 1.0048x; 1.0048x over previous
; DI int opaque_tid() { int t = threadIdx.x; asm volatile("" : "+v"(t)); return t; }
; DI float shx(float v, int mask, int lane) { return __int_as_float(__builtin_amdgcn_ds_bpermute((lane ^ mask) << 2, __float_as_int(v))); }
; template <int VD, bool DIFF>
; DI void attn_dense(const Params& p, const u16* qkv, int ld, u16* o, const float* lam4, const float* subln,
;                            float lam_init, const float* sinks, char* smem) {
;     ...
;   const int tid = opaque_tid(), lane = tid & 63, w = __builtin_amdgcn_readfirstlane(tid >> 6);
;   unsigned* s_stash = (unsigned*)(smem + 2 * TB + 2048) + w * 2048 + lane;
;   const int l31 = lane & 31, hh = lane >> 5;
;   const int q4 = (lane & 15) >> 2, p4 = lane & 3, blk = (lane >> 4) & 1;
;   unsigned char* s_btab = (unsigned char*)(smem + 2 * TB + 2048 + 65536);
;   if (tid < 512) s_relb[tid] = p.relb[tid] * LOG2E;
;   if (tid < 256) s_btab[tid] = (unsigned char)t5_bucket(tid - 128);
;   float* s_sub = (float*)(smem + 2 * TB + 2048 + 65536 + 256);
;   if (DIFF && tid < 128) s_sub[tid] = subln[tid];
;   float lam_full = 0.f;
;   if (DIFF) {
;     float v1 = lam4[lane] * lam4[64 + lane], v2 = lam4[128 + lane] * lam4[192 + lane];
; #pragma unroll
;     for (int o_ = 32; o_ >= 1; o_ >>= 1) { v1 += shx(v1, o_, lane); v2 += shx(v2, o_, lane); }
;     lam_full = __expf(v1) - __expf(v2) + lam_init;
;   }
;   __syncthreads();
;   constexpr int NH = DIFF ? 8 : 16;
;   const int nitems = DIFF ? (256 + 64) : (BATCH * NH * 9);
;   for (int item = blockIdx.x; item < nitems; item += gridDim.x) {
.LBB0_866:
	s_or_b64 exec, exec, s[0:1]
	v_and_b32_e32 v1, 63, v0
	v_readlane_b32 s0, v254, 40
	v_lshlrev_b32_e32 v2, 2, v1
	v_readlane_b32 s1, v254, 41
	s_nop 4
	global_load_dword v3, v2, s[0:1]
	global_load_dword v4, v2, s[0:1] offset:256
	global_load_dword v5, v2, s[0:1] offset:512
	global_load_dword v6, v2, s[0:1] offset:768
	v_xor_b32_e32 v141, 0x80, v2
	s_waitcnt vmcnt(23)
	v_xor_b32_e32 v9, 64, v2
	v_readlane_b32 s0, v253, 5
	v_readlane_b32 s1, v253, 6
	s_andn2_b64 vcc, exec, s[0:1]
	s_waitcnt lgkmcnt(0)
	s_barrier
	s_waitcnt vmcnt(2)
	v_mul_f32_e32 v7, v3, v4
	ds_bpermute_b32 v7, v141, v7
	s_waitcnt vmcnt(0)
	v_mul_f32_e32 v8, v5, v6
	ds_bpermute_b32 v8, v141, v8
	s_waitcnt lgkmcnt(1)
	v_fmac_f32_e32 v7, v3, v4
	ds_bpermute_b32 v3, v9, v7
	s_waitcnt lgkmcnt(1)
	v_fmac_f32_e32 v8, v5, v6
	ds_bpermute_b32 v4, v9, v8
	v_xor_b32_e32 v5, 32, v2
	s_waitcnt lgkmcnt(1)
	v_add_f32_e32 v3, v7, v3
	ds_bpermute_b32 v6, v5, v3
	s_waitcnt lgkmcnt(1)
	v_add_f32_e32 v4, v8, v4
	ds_bpermute_b32 v5, v5, v4
	v_xor_b32_e32 v7, 16, v2
	s_waitcnt lgkmcnt(1)
	v_add_f32_e32 v3, v3, v6
	s_waitcnt lgkmcnt(0)
	v_add_f32_e32 v4, v4, v5
	ds_bpermute_b32 v5, v7, v3
	ds_bpermute_b32 v6, v7, v4
	v_xor_b32_e32 v7, 8, v2
	s_waitcnt lgkmcnt(1)
	v_add_f32_e32 v3, v3, v5
	s_waitcnt lgkmcnt(0)
	v_add_f32_e32 v4, v4, v6
	ds_bpermute_b32 v5, v7, v3
	ds_bpermute_b32 v6, v7, v4
	v_xor_b32_e32 v7, 4, v2
	s_waitcnt lgkmcnt(1)
	v_add_f32_e32 v3, v3, v5
	s_waitcnt lgkmcnt(0)
	v_add_f32_e32 v4, v4, v6
	ds_bpermute_b32 v5, v7, v3
	ds_bpermute_b32 v6, v7, v4
	s_cbranch_vccnz .LBB0_901
	s_waitcnt lgkmcnt(1)
	v_add_f32_e32 v3, v3, v5
	s_waitcnt lgkmcnt(0)
	v_add_f32_e32 v4, v4, v6
	v_mul_f32_e32 v3, 0x3fb8aa3b, v3
	v_mul_f32_e32 v4, 0x3fb8aa3b, v4
	v_exp_f32_e32 v3, v3
	v_exp_f32_e32 v4, v4
	v_lshrrev_b32_e32 v1, 5, v1
	v_ashrrev_i32_e32 v138, 3, v0
	s_movk_i32 s0, 0x90
	s_ashr_i32 s4, s2, 6
	s_ashr_i32 s30, s2, 7
	v_lshlrev_b32_e32 v134, 4, v1
	v_mov_b32_e32 v135, v165
	v_mul_lo_u32 v144, v138, s0
	s_movk_i32 s0, 0x140
	v_sub_f32_e32 v3, v3, v4
	v_lshl_or_b32 v145, s4, 13, v2
	s_add_i32 s30, s30, -3
	v_lshl_add_u64 v[136:137], s[24:25], 0, v[134:135]
	v_mul_lo_u32 v135, v138, s0
	s_movk_i32 s0, 0xb0
	v_add_f32_e32 v143, v220, v3
	v_mad_u64_u32 v[2:3], s[0:1], v138, s0, v[144:145]
	s_cmp_lt_u32 s2, 64
	s_cselect_b64 s[0:1], -1, 0
	s_lshl_b32 s40, s4, 5
	v_readlane_b32 s4, v255, 45
	v_and_b32_e32 v132, 31, v0
	v_lshrrev_b32_e32 v4, 2, v0
	v_lshlrev_b32_e32 v164, 3, v1
	v_and_b32_e32 v5, 7, v0
	v_lshlrev_b32_e32 v169, 2, v1
	v_readlane_b32 s5, v255, 46
	v_lshlrev_b32_e32 v142, 4, v5
	v_lshlrev_b32_e32 v168, 5, v5
	v_and_or_b32 v1, v4, 3, v169
	v_lshlrev_b32_e32 v3, 1, v0
	v_lshlrev_b32_e32 v0, 3, v0
	v_cmp_gt_u32_e32 vcc, 16, v132
	v_lshl_add_u64 v[148:149], s[4:5], 0, v[164:165]
	v_readlane_b32 s4, v252, 0
	v_add_u32_e32 v147, 0xf000, v145
	v_mov_b32_e32 v133, v165
	v_ashrrev_i32_e32 v139, 31, v138
	v_lshlrev_b32_e32 v140, 3, v5
	v_and_b32_e32 v170, 32, v3
	v_and_b32_e32 v146, 24, v0
	s_and_b64 s[0:1], s[0:1], vcc
	s_add_i32 s41, s40, 0xffffff10
	v_mul_u32_u24_e32 v171, 0x90, v132
	v_mul_u32_u24_e32 v172, 0x140, v1
	v_or_b32_e32 v173, 0x1f100, v134
	v_or_b32_e32 v174, 0x1f120, v134
	v_or_b32_e32 v175, 0x1f140, v134
	v_or_b32_e32 v176, 0x1f160, v134
	v_or_b32_e32 v177, 0x1f180, v134
	v_or_b32_e32 v178, 0x1f1a0, v134
	v_or_b32_e32 v179, 0x1f1c0, v134
	v_or_b32_e32 v180, 0x1f1e0, v134
	v_or_b32_e32 v181, 0x1f200, v134
	v_or_b32_e32 v182, 0x1f220, v134
	v_or_b32_e32 v183, 0x1f240, v134
	v_or_b32_e32 v184, 0x1f260, v134
	v_or_b32_e32 v185, 0x1f280, v134
	v_or_b32_e32 v186, 0x1f2a0, v134
	v_or_b32_e32 v187, 0x1f2c0, v134
	v_or_b32_e32 v188, 0x1f2e0, v134
	v_add_u32_e32 v189, v144, v142
	v_add_u32_e32 v190, v2, v168
	s_mov_b32 s42, s4
	v_readlane_b32 s5, v252, 1
	v_readfirstlane_b32 vcc_lo, v210
	s_nop 1
	s_cmp_lt_u32 vcc_lo, 0x100
	s_cbranch_scc1 .Lattn_prio_skip
	s_setprio 1
.Lattn_prio_skip:
	s_branch .LBB0_869
.LBB0_868:
	v_readlane_b32 s4, v254, 24
	v_readlane_b32 s6, v254, 26
	s_add_i32 s42, s42, s6
	s_cmpk_gt_i32 s42, 0x13f
	v_readlane_b32 s5, v254, 25
	v_readlane_b32 s7, v254, 27
	s_cbranch_scc1 .LBB0_901

; DI unsigned xb_add(unsigned* p, unsigned v) { return __hip_atomic_fetch_add(p, v, __ATOMIC_RELAXED, __HIP_MEMORY_SCOPE_AGENT); }
; DI void xcd_barrier(const XcdBarrier& b) {
;   asm volatile("s_waitcnt vmcnt(0)" ::: "memory");
;   __syncthreads();
;   if (threadIdx.x == 0) {
;     unsigned* bar = b.bar;
;     __builtin_amdgcn_s_waitcnt(0);
;     unsigned nloc = b.st[0], nx = b.st[1];
;     if (nloc == 0u) { xcd_barrier_complete(bar, b.x, nloc, nx); b.st[0] = nloc; b.st[1] = nx; }
;     const unsigned old = xb_add(&bar[XB_XSUB(b.x)], 1u);
.LBB0_921:
	v_readlane_b32 s0, v254, 38
	v_readlane_b32 s1, v254, 34
	v_readlane_b32 s24, v254, 24
	s_or_b32 s0, s1, s0
	v_readlane_b32 s25, v254, 25
	s_cmp_lg_u32 s0, 0
	v_readlane_b32 s26, v254, 26
	v_readlane_b32 s27, v254, 27
	s_nop 0
	s_waitcnt vmcnt(0)
	s_waitcnt lgkmcnt(0)
	s_setprio 0
	s_barrier
	s_mov_b64 s[0:1], exec
	v_readlane_b32 s4, v252, 4
	v_readlane_b32 s5, v252, 5
	s_and_b64 s[4:5], s[0:1], s[4:5]
	s_mov_b64 exec, s[4:5]
	s_cbranch_execz .LBB0_975
	s_waitcnt vmcnt(0) expcnt(0) lgkmcnt(0)
	ds_read_b32 v2, v212
	ds_read_b32 v0, v213
	s_waitcnt lgkmcnt(1)
	v_cmp_ne_u32_e32 vcc, 0, v2
	s_cbranch_vccnz .LBB0_939
	s_mov_b32 s2, 1
	s_branch .LBB0_926
